# attention item epilogue gate words fetched during the item's last key pair
# speedup vs baseline: 1.1111x; 1.0036x over previous
; DI int otid() { int t = threadIdx.x; asm volatile("" : "+v"(t)); return t; }
; DI void phase_mix(KP p, int l, char* lds) {
;     ...
;   const bool upd = (l == 0);
;   const float sbA = ((const float*)(ws + WS_SBND))[l * 2], sbB = ((const float*)(ws + WS_SBND))[l * 2 + 1];
;   const int xcd = blockIdx.x & 7, lb = 2 * (blockIdx.x >> 3) + __builtin_amdgcn_readfirstlane(otid() >> 8), nlb = 2 * (gridDim.x >> 3);
;   const int nDL = 64, nA = 0, nB = 0, nDC = upd ? 8 : 0, nAc = 0, nBc = 0, nCM = 72, nFN = upd ? 72 : 64;
;   const int e0 = nDL, e1 = e0 + nA, e2 = e1 + nB, e3 = e2 + nDC, e4 = e3 + nAc, e5 = e4 + nBc, e6 = e5 + nCM, e7 = e6 + nFN;
;   unsigned* cnt = (unsigned*)(ws + WS_CNT) + l * 288;
;   const bf16_t* wf = (const bf16_t*)(ws + WS_WF) + (size_t)l * 256 * 256;
;   {
;     const int lbw = blockIdx.x >> 3, nlbw = gridDim.x >> 3;
;     const int nW = upd ? 144 : 128;
;     for (int it = lbw; it < nW; it += nlbw) {
;       const bool isA = (it < 64) || (it >= 128 && it < 136);
;       int b, hd, q0, k0, nk;
;       if (it < 128) { const int i2 = it & 63; b = 2 * xcd + (i2 >> 5); hd = (i2 >> 3) & 3; q0 = (i2 & 7) * 256; k0 = 0; nk = T; }
;       else { const int i2 = (it - 128) & 7; b = 2 * xcd + (i2 >> 2); hd = i2 & 3; q0 = SEQ; k0 = SEQ; nk = CL; }
;       const size_t r0 = (size_t)b * T + q0; const size_t bh = (size_t)b * 4 + hd, bk = (size_t)b * 2 + (hd >> 1);
;       if (isA) {
;         if (sbA <= 30.f) attn_item8<96, true>(QA + (bh * T + q0) * 96, KA + (bh * T + k0) * 96, VAT + bh * 64 * T + k0, nk, lds, P + r0 * NIN + O_GA + 64 * hd, Y + r0 * 1024 + 64 * hd, sbA);
; __global__ void __launch_bounds__(NTHR, 2) fwd_megakernel(Params p_byval) {
;     ...
;   for (int ph = p->ph_lo; ph < p->ph_hi; ++ph) {
;     asm volatile("" : "+s"(p));
;     if (ph == 0) phase0(p, lds);
;     else {
;       const int l = (ph - 1) / 7, s = (ph - 1) % 7;
;       switch (s) {
;         case 0: phase_norm(p, l); break;
;         case 1: phase_inproj(p, l, lds); break;
;         case 2: phase_feat_a(p, l, lds); break;
;         case 3: phase_feat_b(p, l, lds); break;
;         case 4: phase_feat_c(p, l); break;
;         case 5: phase_mix(p, l, lds); break;
.LBB0_22:
	v_readlane_b32 s4, v253, 2
	v_readlane_b32 s5, v253, 3
	s_cmp_lg_u32 s4, 0
	s_mov_b64 s[4:5], -1
	s_cbranch_scc0 .LBB0_284
	v_readlane_b32 s4, v253, 2
	s_add_i32 s2, s4, -1
	s_mul_hi_i32 s4, s2, 0x92492493
	v_readlane_b32 s5, v253, 3
	s_add_i32 s4, s4, s2
	s_lshr_b32 s5, s4, 31
	s_ashr_i32 s4, s4, 2
	s_add_i32 s4, s4, s5
	s_mov_b32 s14, s4
	s_mul_i32 s4, s4, 7
	s_sub_i32 s2, s2, s4
	s_load_dwordx2 s[4:5], s[0:1], 0xb8
	v_writelane_b32 v255, s14, 26
	s_cmp_lt_i32 s2, 3
	s_mov_b64 s[44:45], 0
	v_writelane_b32 v255, s15, 27
	s_waitcnt lgkmcnt(0)
	v_writelane_b32 v255, s4, 28
	s_nop 1
	v_writelane_b32 v255, s5, 29
	s_mov_b64 s[4:5], -1
	v_writelane_b32 v255, s2, 30
	s_cbranch_scc1 .LBB0_256
	v_readlane_b32 s2, v255, 30
	s_cmp_gt_i32 s2, 3
	s_cbranch_scc0 .LBB0_215
	s_cmp_gt_i32 s2, 4
	s_cbranch_scc0 .LBB0_182
	s_cmp_eq_u32 s2, 5
	s_mov_b64 s[44:45], -1
	s_cbranch_scc0 .LBB0_181
	s_load_dwordx2 s[18:19], s[0:1], 0xb8
	s_waitcnt lgkmcnt(0)
	s_add_u32 s42, s18, 0x60b5100
	s_addc_u32 s43, s19, 0
	s_add_u32 s2, s18, 0x18b5100
	v_writelane_b32 v255, s2, 31
	s_addc_u32 s2, s19, 0
	v_readlane_b32 s4, v253, 2
	v_writelane_b32 v255, s2, 32
	v_readlane_b32 s5, v253, 3
	s_add_i32 s2, s4, -8
	v_readlane_b32 s4, v255, 26
	v_readlane_b32 s5, v255, 27
	s_lshl_b32 s4, s4, 1
	s_ashr_i32 s5, s4, 31
	s_lshl_b64 s[4:5], s[4:5], 2
	s_add_u32 s4, s18, s4
	v_writelane_b32 v255, s18, 33
	s_addc_u32 s5, s19, s5
	v_mov_b32_e32 v0, s4
	v_add_co_u32_e32 v2, vcc, 0x69000, v0
	v_mov_b32_e32 v0, s5
	s_nop 0
	v_addc_co_u32_e32 v3, vcc, 0, v0, vcc
	s_waitcnt vmcnt(0)
	global_load_dwordx2 v[18:19], v[2:3], off
	s_cmp_lt_u32 s2, -13
	v_writelane_b32 v255, s19, 34
	s_cselect_b64 s[4:5], -1, 0
	v_writelane_b32 v255, s4, 35
	s_movk_i32 s2, 0x90
	v_mov_b32_e32 v0, v196
	v_writelane_b32 v255, s5, 36
	s_and_b64 s[4:5], s[4:5], exec
	s_cselect_b32 s75, 0x80, s2
	v_readlane_b32 s2, v254, 42
	s_cmp_ge_u32 s2, s75
	v_readfirstlane_b32 s2, v0
	s_nop 1
	v_writelane_b32 v255, s2, 37
	s_cbranch_scc1 .LBB0_123
	v_readlane_b32 s4, v255, 33
	v_readlane_b32 s5, v255, 34
	s_add_u32 s2, s4, 0x16175100
	v_writelane_b32 v255, s2, 38
	s_addc_u32 s2, s5, 0
	v_writelane_b32 v255, s2, 39
	s_add_u32 s2, s4, 0x17c75100
	v_writelane_b32 v255, s2, 40
	s_addc_u32 s2, s5, 0
	v_writelane_b32 v255, s2, 41
	s_add_u32 s2, s4, 0x19775100
	v_writelane_b32 v255, s2, 42
	s_addc_u32 s2, s5, 0
	v_writelane_b32 v255, s2, 43
	s_add_u32 s2, s4, 0x1a975100
	v_writelane_b32 v255, s2, 44
	s_addc_u32 s2, s5, 0
	v_writelane_b32 v255, s2, 45
	s_add_u32 s2, s4, 0x1bb75100
	v_writelane_b32 v255, s2, 47
	s_addc_u32 s2, s5, 0
	v_writelane_b32 v255, s2, 48
	s_add_u32 s2, s4, 0x1c475100
	v_writelane_b32 v255, s2, 49
	s_addc_u32 s2, s5, 0
	v_writelane_b32 v255, s2, 50
	s_mov_b32 s2, 0x41f00000
	s_waitcnt vmcnt(0) lgkmcnt(0)
	v_cmp_ge_f32_e64 s[4:5], s2, v19
	v_xor_b32_e32 v2, 0x80000000, v19
	v_mov_b32_e32 v3, v2
	v_writelane_b32 v255, s4, 51
	v_mov_b32_e32 v4, v2
	v_mov_b32_e32 v5, v2
	v_writelane_b32 v255, s5, 52
	v_cmp_ge_f32_e64 s[4:5], s2, v18
	v_xor_b32_e32 v18, 0x80000000, v18
	v_mov_b32_e32 v6, v2
	v_writelane_b32 v255, s4, 53
	v_mov_b32_e32 v7, v2
	v_mov_b32_e32 v8, v2
	v_writelane_b32 v255, s5, 54
	v_mov_b32_e32 v9, v2
	v_mov_b32_e32 v10, v2
	v_mov_b32_e32 v11, v2
	v_mov_b32_e32 v12, v2
	v_mov_b32_e32 v13, v2
	v_mov_b32_e32 v14, v2
	v_mov_b32_e32 v15, v2
	v_mov_b32_e32 v16, v2
	v_mov_b32_e32 v17, v2
	v_mov_b32_e32 v19, v18
	v_mov_b32_e32 v20, v18
	v_mov_b32_e32 v21, v18
	v_mov_b32_e32 v22, v18
	v_mov_b32_e32 v23, v18
	v_mov_b32_e32 v24, v18
	v_mov_b32_e32 v25, v18
	v_mov_b32_e32 v26, v18
	v_mov_b32_e32 v27, v18
	v_mov_b32_e32 v28, v18
	v_mov_b32_e32 v29, v18
	v_mov_b32_e32 v30, v18
	v_mov_b32_e32 v31, v18
	v_mov_b32_e32 v32, v18
	v_mov_b32_e32 v33, v18
	s_mov_b32 s100, 0
	v_readlane_b32 s64, v254, 42
	v_writelane_b32 v255, s75, 55
	s_branch .LBB0_32

; DI float silu(float x) { return x / (1.f + __expf(-x)); }
; DI f32x4 unpack4(u32x2 v) { f32x4 r = {bflo(v.x), bfhi(v.x), bflo(v.y), bfhi(v.y)}; return r; }
; DI u32x2 pack4(f32x4 v) { u32x2 r = {cvtpk(v[0], v[1]), cvtpk(v[2], v[3])}; return r; }
; template <int DQK, bool STATIC>
; DI void attn_item8(const bf16_t* __restrict__ Q, const bf16_t* __restrict__ Kp, const bf16_t* __restrict__ Vt, int nkeys, char* lds,
;                   const bf16_t* __restrict__ Pg, bf16_t* __restrict__ Yg  , float mfix) {
;     ...
;   const float lt = l_run + __shfl_xor(l_run, 32);
;   const float inv = 1.f / lt;
;   const size_t rq = (size_t)(32 * w + l31);
; #pragma unroll
;   for (int d = 0; d < 2; ++d)
; #pragma unroll
;     for (int q = 0; q < 4; ++q) {
;       const int dv = 32 * d + 8 * q + 4 * h;
;       f32x4 g = unpack4(*(const u32x2*)(Pg + rq * NIN + dv));
;       f32x4 v = {o[d][4 * q] * inv * silu(g[0]), o[d][4 * q + 1] * inv * silu(g[1]), o[d][4 * q + 2] * inv * silu(g[2]), o[d][4 * q + 3] * inv * silu(g[3])};
;       *(u32x2*)(Yg + rq * 1024 + dv) = pack4(v);
.LBB0_31:
	s_waitcnt lgkmcnt(0)
	v_add_f32_e32 v0, v215, v0
	v_div_scale_f32 v66, s[4:5], v0, v0, 1.0
	v_rcp_f32_e32 v67, v66
	v_readlane_b32 s69, v255, 25
	s_add_i32 s64, s64, s69
	s_cmp_ge_u32 s64, s75
	v_fma_f32 v68, -v66, v67, 1.0
	v_fmac_f32_e32 v67, v68, v67
	v_div_scale_f32 v68, vcc, 1.0, v0, 1.0
	v_mul_f32_e32 v69, v68, v67
	v_fma_f32 v70, -v66, v69, v68
	v_fmac_f32_e32 v69, v70, v67
	v_fma_f32 v66, -v66, v69, v68
	v_div_fmas_f32 v66, v66, v67, v69
	v_mov_b64_e32 v[68:69], s[36:37]
	v_mad_u64_u32 v[68:69], s[4:5], v188, s11, v[68:69]
	v_div_fixup_f32 v66, v66, v0, 1.0
	v_mov_b32_e32 v0, v69
	v_mad_u64_u32 v[70:71], s[4:5], v189, s11, v[0:1]
	v_mov_b32_e32 v69, v70
	v_lshlrev_b32_e32 v0, 3, v187
	v_lshl_add_u64 v[68:69], v[68:69], 0, v[0:1]
	s_cmp_lg_u32 s100, 1
	s_cbranch_scc0 .Lepi_skipld
	global_load_dwordx2 v[112:113], v[68:69], off
	global_load_dwordx2 v[114:115], v[68:69], off offset:16
	global_load_dwordx2 v[116:117], v[68:69], off offset:32
	global_load_dwordx2 v[118:119], v[68:69], off offset:48
	global_load_dwordx2 v[120:121], v[68:69], off offset:64
	global_load_dwordx2 v[122:123], v[68:69], off offset:80
	global_load_dwordx2 v[124:125], v[68:69], off offset:96
	global_load_dwordx2 v[126:127], v[68:69], off offset:112
.Lepi_skipld:
	s_mov_b32 s100, 0
	s_cmp_ge_u32 s64, s75
	v_lshlrev_b64 v[70:71], 11, v[188:189]
	v_lshl_add_u64 v[70:71], s[40:41], 0, v[70:71]
	v_mov_b32_e32 v187, v202
	s_waitcnt vmcnt(0)
	v_mov_b32_e32 v72, v112
	v_mov_b32_e32 v73, v113
	v_lshlrev_b32_e32 v67, 16, v72
	v_and_b32_e32 v72, 0xffff0000, v72
	v_mul_f32_e32 v74, 0xbfb8aa3b, v67
	v_mul_f32_e32 v75, 0xbfb8aa3b, v72
	v_exp_f32_e32 v74, v74
	v_exp_f32_e32 v75, v75
	v_pk_mul_f32 v[50:51], v[66:67], v[50:51] op_sel_hi:[0,1]
	v_pk_add_f32 v[74:75], v[74:75], 1.0 op_sel_hi:[1,0]
	s_nop 0
	v_div_scale_f32 v76, s[4:5], v75, v75, v72
	v_rcp_f32_e32 v77, v76
	s_nop 0
	v_fma_f32 v78, -v76, v77, 1.0
	v_fmac_f32_e32 v77, v78, v77
	v_div_scale_f32 v78, vcc, v72, v75, v72
	v_mul_f32_e32 v79, v78, v77
	v_fma_f32 v80, -v76, v79, v78
	v_fmac_f32_e32 v79, v80, v77
	v_fma_f32 v76, -v76, v79, v78
	v_div_fmas_f32 v76, v76, v77, v79
	v_div_fixup_f32 v75, v76, v75, v72
	v_div_scale_f32 v72, s[4:5], v74, v74, v67
	v_rcp_f32_e32 v76, v72
	s_nop 0
	v_fma_f32 v77, -v72, v76, 1.0
	v_fmac_f32_e32 v76, v77, v76
	v_div_scale_f32 v77, vcc, v67, v74, v67
	v_mul_f32_e32 v78, v77, v76
	v_fma_f32 v79, -v72, v78, v77
	v_fmac_f32_e32 v78, v79, v76
	v_fma_f32 v72, -v72, v78, v77
	v_div_fmas_f32 v72, v72, v76, v78
	v_div_fixup_f32 v74, v72, v74, v67
	v_pk_mul_f32 v[50:51], v[50:51], v[74:75]
	v_lshlrev_b32_e32 v67, 16, v73
	v_and_b32_e32 v74, 0xffff0000, v73
	v_mul_f32_e32 v72, 0xbfb8aa3b, v67
	v_mul_f32_e32 v73, 0xbfb8aa3b, v74
	v_exp_f32_e32 v72, v72
	v_exp_f32_e32 v73, v73
	v_pk_mul_f32 v[52:53], v[66:67], v[52:53] op_sel_hi:[0,1]
	v_pk_add_f32 v[72:73], v[72:73], 1.0 op_sel_hi:[1,0]
	s_nop 0
	v_div_scale_f32 v75, s[4:5], v73, v73, v74
	v_rcp_f32_e32 v76, v75
	s_nop 0
	v_fma_f32 v77, -v75, v76, 1.0
	v_fmac_f32_e32 v76, v77, v76
	v_div_scale_f32 v77, vcc, v74, v73, v74
	v_mul_f32_e32 v78, v77, v76
	v_fma_f32 v79, -v75, v78, v77
	v_fmac_f32_e32 v78, v79, v76
	v_fma_f32 v75, -v75, v78, v77
	v_div_fmas_f32 v75, v75, v76, v78
	v_div_fixup_f32 v73, v75, v73, v74
	v_div_scale_f32 v74, s[4:5], v72, v72, v67
	v_rcp_f32_e32 v75, v74
	s_nop 0
	v_fma_f32 v76, -v74, v75, 1.0
	v_fmac_f32_e32 v75, v76, v75
	v_div_scale_f32 v76, vcc, v67, v72, v67
	v_mul_f32_e32 v77, v76, v75
	v_fma_f32 v78, -v74, v77, v76
	v_fmac_f32_e32 v77, v78, v75
	v_fma_f32 v74, -v74, v77, v76
	v_div_fmas_f32 v74, v74, v75, v77
	v_div_fixup_f32 v72, v74, v72, v67
	v_pk_mul_f32 v[72:73], v[52:53], v[72:73]
	v_cvt_pk_bf16_f32 v52, v50, v51
	v_cvt_pk_bf16_f32 v53, v72, v73
	v_lshl_add_u64 v[50:51], v[70:71], 0, v[0:1]
	global_store_dwordx2 v[50:51], v[52:53], off
	v_mov_b32_e32 v70, v114
	v_mov_b32_e32 v71, v115
	v_lshlrev_b32_e32 v0, 16, v70
	v_and_b32_e32 v67, 0xffff0000, v70
	v_mul_f32_e32 v52, 0xbfb8aa3b, v0
	v_mul_f32_e32 v53, 0xbfb8aa3b, v67
	v_exp_f32_e32 v52, v52
	v_exp_f32_e32 v53, v53
	v_pk_mul_f32 v[54:55], v[66:67], v[54:55] op_sel_hi:[0,1]
	v_pk_add_f32 v[52:53], v[52:53], 1.0 op_sel_hi:[1,0]
	s_nop 0
	v_div_scale_f32 v70, s[4:5], v53, v53, v67
	v_rcp_f32_e32 v72, v70
	s_nop 0
	v_fma_f32 v73, -v70, v72, 1.0
	v_fmac_f32_e32 v72, v73, v72
	v_div_scale_f32 v73, vcc, v67, v53, v67
	v_mul_f32_e32 v74, v73, v72
	v_fma_f32 v75, -v70, v74, v73
	v_fmac_f32_e32 v74, v75, v72
	v_fma_f32 v70, -v70, v74, v73
	v_div_fmas_f32 v70, v70, v72, v74
	v_div_fixup_f32 v53, v70, v53, v67
	v_div_scale_f32 v67, s[4:5], v52, v52, v0
	v_rcp_f32_e32 v70, v67
	s_nop 0
	v_fma_f32 v72, -v67, v70, 1.0
	v_fmac_f32_e32 v70, v72, v70
	v_div_scale_f32 v72, vcc, v0, v52, v0
	v_mul_f32_e32 v73, v72, v70
	v_fma_f32 v74, -v67, v73, v72
	v_fmac_f32_e32 v73, v74, v70
	v_fma_f32 v67, -v67, v73, v72
	v_div_fmas_f32 v67, v67, v70, v73
	v_div_fixup_f32 v52, v67, v52, v0
	v_lshlrev_b32_e32 v0, 16, v71
	v_pk_mul_f32 v[52:53], v[54:55], v[52:53]
	v_and_b32_e32 v67, 0xffff0000, v71
	v_mul_f32_e32 v54, 0xbfb8aa3b, v0
	v_exp_f32_e32 v70, v54
	v_pk_mul_f32 v[54:55], v[66:67], v[56:57] op_sel_hi:[0,1]
	v_mul_f32_e32 v56, 0xbfb8aa3b, v67
	v_exp_f32_e32 v71, v56
	v_cvt_pk_bf16_f32 v52, v52, v53
	v_pk_add_f32 v[56:57], v[70:71], 1.0 op_sel_hi:[1,0]
	s_nop 0
	v_div_scale_f32 v70, s[4:5], v57, v57, v67
	v_rcp_f32_e32 v71, v70
	s_nop 0
	v_fma_f32 v72, -v70, v71, 1.0
	v_fmac_f32_e32 v71, v72, v71
	v_div_scale_f32 v72, vcc, v67, v57, v67
	v_mul_f32_e32 v73, v72, v71
	v_fma_f32 v74, -v70, v73, v72
	v_fmac_f32_e32 v73, v74, v71
	v_fma_f32 v70, -v70, v73, v72
; DI float silu(float x) { return x / (1.f + __expf(-x)); }
; DI f32x4 unpack4(u32x2 v) { f32x4 r = {bflo(v.x), bfhi(v.x), bflo(v.y), bfhi(v.y)}; return r; }
; DI u32x2 pack4(f32x4 v) { u32x2 r = {cvtpk(v[0], v[1]), cvtpk(v[2], v[3])}; return r; }
; template <int DQK, bool STATIC>
; DI void attn_item8(const bf16_t* __restrict__ Q, const bf16_t* __restrict__ Kp, const bf16_t* __restrict__ Vt, int nkeys, char* lds,
;                   const bf16_t* __restrict__ Pg, bf16_t* __restrict__ Yg  , float mfix) {
;     ...
; #pragma unroll
;   for (int d = 0; d < 2; ++d)
; #pragma unroll
;     for (int q = 0; q < 4; ++q) {
;       const int dv = 32 * d + 8 * q + 4 * h;
;       f32x4 g = unpack4(*(const u32x2*)(Pg + rq * NIN + dv));
;       f32x4 v = {o[d][4 * q] * inv * silu(g[0]), o[d][4 * q + 1] * inv * silu(g[1]), o[d][4 * q + 2] * inv * silu(g[2]), o[d][4 * q + 3] * inv * silu(g[3])};
;       *(u32x2*)(Yg + rq * 1024 + dv) = pack4(v);
;     }
	v_div_fmas_f32 v70, v70, v71, v73
	v_div_fixup_f32 v57, v70, v57, v67
	v_div_scale_f32 v67, s[4:5], v56, v56, v0
	v_rcp_f32_e32 v70, v67
	s_nop 0
	v_fma_f32 v71, -v67, v70, 1.0
	v_fmac_f32_e32 v70, v71, v70
	v_div_scale_f32 v71, vcc, v0, v56, v0
	v_mul_f32_e32 v72, v71, v70
	v_fma_f32 v73, -v67, v72, v71
	v_fmac_f32_e32 v72, v73, v70
	v_fma_f32 v67, -v67, v72, v71
	v_div_fmas_f32 v67, v67, v70, v72
	v_div_fixup_f32 v56, v67, v56, v0
	v_pk_mul_f32 v[54:55], v[54:55], v[56:57]
	v_pk_mul_f32 v[56:57], v[66:67], v[58:59] op_sel_hi:[0,1]
	v_cvt_pk_bf16_f32 v53, v54, v55
	global_store_dwordx2 v[50:51], v[52:53], off offset:16
	v_mov_b32_e32 v54, v116
	v_mov_b32_e32 v55, v117
	v_lshlrev_b32_e32 v0, 16, v54
	v_and_b32_e32 v54, 0xffff0000, v54
	v_mul_f32_e32 v52, 0xbfb8aa3b, v0
	v_mul_f32_e32 v53, 0xbfb8aa3b, v54
	v_exp_f32_e32 v52, v52
	v_exp_f32_e32 v53, v53
	s_nop 0
	v_pk_add_f32 v[52:53], v[52:53], 1.0 op_sel_hi:[1,0]
	s_nop 0
	v_div_scale_f32 v58, s[4:5], v53, v53, v54
	v_rcp_f32_e32 v59, v58
	s_nop 0
	v_fma_f32 v67, -v58, v59, 1.0
	v_fmac_f32_e32 v59, v67, v59
	v_div_scale_f32 v67, vcc, v54, v53, v54
	v_mul_f32_e32 v70, v67, v59
	v_fma_f32 v71, -v58, v70, v67
	v_fmac_f32_e32 v70, v71, v59
	v_fma_f32 v58, -v58, v70, v67
	v_div_fmas_f32 v58, v58, v59, v70
	v_div_fixup_f32 v53, v58, v53, v54
	v_div_scale_f32 v54, s[4:5], v52, v52, v0
	v_rcp_f32_e32 v58, v54
	s_nop 0
	v_fma_f32 v59, -v54, v58, 1.0
	v_fmac_f32_e32 v58, v59, v58
	v_div_scale_f32 v59, vcc, v0, v52, v0
	v_mul_f32_e32 v67, v59, v58
	v_fma_f32 v70, -v54, v67, v59
	v_fmac_f32_e32 v67, v70, v58
	v_fma_f32 v54, -v54, v67, v59
	v_div_fmas_f32 v54, v54, v58, v67
	v_div_fixup_f32 v52, v54, v52, v0
	v_lshlrev_b32_e32 v0, 16, v55
	v_and_b32_e32 v58, 0xffff0000, v55
	v_pk_mul_f32 v[52:53], v[56:57], v[52:53]
	v_mul_f32_e32 v54, 0xbfb8aa3b, v0
	v_mul_f32_e32 v57, 0xbfb8aa3b, v58
	v_exp_f32_e32 v56, v54
	v_exp_f32_e32 v57, v57
	v_pk_mul_f32 v[54:55], v[66:67], v[60:61] op_sel_hi:[0,1]
	v_cvt_pk_bf16_f32 v52, v52, v53
	v_pk_add_f32 v[56:57], v[56:57], 1.0 op_sel_hi:[1,0]
	s_nop 0
	v_div_scale_f32 v59, s[4:5], v57, v57, v58
	v_rcp_f32_e32 v60, v59
	s_nop 0
	v_fma_f32 v61, -v59, v60, 1.0
	v_fmac_f32_e32 v60, v61, v60
	v_div_scale_f32 v61, vcc, v58, v57, v58
	v_mul_f32_e32 v67, v61, v60
	v_fma_f32 v70, -v59, v67, v61
	v_fmac_f32_e32 v67, v70, v60
	v_fma_f32 v59, -v59, v67, v61
	v_div_fmas_f32 v59, v59, v60, v67
	v_div_fixup_f32 v57, v59, v57, v58
	v_div_scale_f32 v58, s[4:5], v56, v56, v0
	v_rcp_f32_e32 v59, v58
	s_nop 0
	v_fma_f32 v60, -v58, v59, 1.0
	v_fmac_f32_e32 v59, v60, v59
	v_div_scale_f32 v60, vcc, v0, v56, v0
	v_mul_f32_e32 v61, v60, v59
	v_fma_f32 v67, -v58, v61, v60
	v_fmac_f32_e32 v61, v67, v59
	v_fma_f32 v58, -v58, v61, v60
	v_div_fmas_f32 v58, v58, v59, v61
	v_div_fixup_f32 v56, v58, v56, v0
	v_pk_mul_f32 v[54:55], v[54:55], v[56:57]
	v_pk_mul_f32 v[56:57], v[66:67], v[62:63] op_sel_hi:[0,1]
	v_cvt_pk_bf16_f32 v53, v54, v55
	global_store_dwordx2 v[50:51], v[52:53], off offset:32
	v_mov_b32_e32 v54, v118
	v_mov_b32_e32 v55, v119
	v_pk_mul_f32 v[34:35], v[66:67], v[34:35] op_sel_hi:[0,1]
	v_pk_mul_f32 v[36:37], v[66:67], v[36:37] op_sel_hi:[0,1]
	v_pk_mul_f32 v[38:39], v[66:67], v[38:39] op_sel_hi:[0,1]
	v_lshlrev_b32_e32 v0, 16, v54
	v_and_b32_e32 v54, 0xffff0000, v54
	v_mul_f32_e32 v52, 0xbfb8aa3b, v0
	v_mul_f32_e32 v53, 0xbfb8aa3b, v54
	v_exp_f32_e32 v52, v52
	v_exp_f32_e32 v53, v53
	s_nop 0
	v_pk_add_f32 v[52:53], v[52:53], 1.0 op_sel_hi:[1,0]
	s_nop 0
	v_div_scale_f32 v58, s[4:5], v53, v53, v54
	v_rcp_f32_e32 v59, v58
	s_nop 0
	v_fma_f32 v60, -v58, v59, 1.0
	v_fmac_f32_e32 v59, v60, v59
	v_div_scale_f32 v60, vcc, v54, v53, v54
	v_mul_f32_e32 v61, v60, v59
	v_fma_f32 v62, -v58, v61, v60
	v_fmac_f32_e32 v61, v62, v59
	v_fma_f32 v58, -v58, v61, v60
	v_div_fmas_f32 v58, v58, v59, v61
	v_div_fixup_f32 v53, v58, v53, v54
	v_div_scale_f32 v54, s[4:5], v52, v52, v0
	v_rcp_f32_e32 v58, v54
	s_nop 0
	v_fma_f32 v59, -v54, v58, 1.0
	v_fmac_f32_e32 v58, v59, v58
	v_div_scale_f32 v59, vcc, v0, v52, v0
	v_mul_f32_e32 v60, v59, v58
	v_fma_f32 v61, -v54, v60, v59
	v_fmac_f32_e32 v60, v61, v58
	v_fma_f32 v54, -v54, v60, v59
	v_div_fmas_f32 v54, v54, v58, v60
	v_div_fixup_f32 v52, v54, v52, v0
	v_lshlrev_b32_e32 v0, 16, v55
	v_and_b32_e32 v58, 0xffff0000, v55
	v_pk_mul_f32 v[52:53], v[56:57], v[52:53]
	v_mul_f32_e32 v54, 0xbfb8aa3b, v0
	v_mul_f32_e32 v57, 0xbfb8aa3b, v58
	v_exp_f32_e32 v56, v54
	v_exp_f32_e32 v57, v57
	v_pk_mul_f32 v[54:55], v[66:67], v[64:65] op_sel_hi:[0,1]
	v_cvt_pk_bf16_f32 v52, v52, v53
	v_pk_add_f32 v[56:57], v[56:57], 1.0 op_sel_hi:[1,0]
	s_nop 0
	v_div_scale_f32 v59, s[4:5], v57, v57, v58
	v_rcp_f32_e32 v60, v59
	s_nop 0
	v_fma_f32 v61, -v59, v60, 1.0
	v_fmac_f32_e32 v60, v61, v60
	v_div_scale_f32 v61, vcc, v58, v57, v58
	v_mul_f32_e32 v62, v61, v60
	v_fma_f32 v63, -v59, v62, v61
	v_fmac_f32_e32 v62, v63, v60
	v_fma_f32 v59, -v59, v62, v61
	v_div_fmas_f32 v59, v59, v60, v62
	v_div_fixup_f32 v57, v59, v57, v58
	v_div_scale_f32 v58, s[4:5], v56, v56, v0
	v_rcp_f32_e32 v59, v58
	s_nop 0
	v_fma_f32 v60, -v58, v59, 1.0
	v_fmac_f32_e32 v59, v60, v59
	v_div_scale_f32 v60, vcc, v0, v56, v0
	v_mul_f32_e32 v61, v60, v59
	v_fma_f32 v62, -v58, v61, v60
	v_fmac_f32_e32 v61, v62, v59
	v_fma_f32 v58, -v58, v61, v60
	v_div_fmas_f32 v58, v58, v59, v61
	v_div_fixup_f32 v56, v58, v56, v0
	v_pk_mul_f32 v[54:55], v[54:55], v[56:57]
	s_nop 0
	v_cvt_pk_bf16_f32 v53, v54, v55
	global_store_dwordx2 v[50:51], v[52:53], off offset:48
	v_mov_b32_e32 v52, v120
	v_mov_b32_e32 v53, v121
	v_lshlrev_b32_e32 v0, 16, v52
	v_and_b32_e32 v52, 0xffff0000, v52
	v_mul_f32_e32 v54, 0xbfb8aa3b, v0
; DI float silu(float x) { return x / (1.f + __expf(-x)); }
; DI f32x4 unpack4(u32x2 v) { f32x4 r = {bflo(v.x), bfhi(v.x), bflo(v.y), bfhi(v.y)}; return r; }
; DI u32x2 pack4(f32x4 v) { u32x2 r = {cvtpk(v[0], v[1]), cvtpk(v[2], v[3])}; return r; }
; template <int DQK, bool STATIC>
; DI void attn_item8(const bf16_t* __restrict__ Q, const bf16_t* __restrict__ Kp, const bf16_t* __restrict__ Vt, int nkeys, char* lds,
;                   const bf16_t* __restrict__ Pg, bf16_t* __restrict__ Yg  , float mfix) {
;     ...
; #pragma unroll
;   for (int d = 0; d < 2; ++d)
; #pragma unroll
;     for (int q = 0; q < 4; ++q) {
;       const int dv = 32 * d + 8 * q + 4 * h;
;       f32x4 g = unpack4(*(const u32x2*)(Pg + rq * NIN + dv));
;       f32x4 v = {o[d][4 * q] * inv * silu(g[0]), o[d][4 * q + 1] * inv * silu(g[1]), o[d][4 * q + 2] * inv * silu(g[2]), o[d][4 * q + 3] * inv * silu(g[3])};
;       *(u32x2*)(Yg + rq * 1024 + dv) = pack4(v);
;     }
	v_mul_f32_e32 v55, 0xbfb8aa3b, v52
	v_exp_f32_e32 v54, v54
	v_exp_f32_e32 v55, v55
	s_nop 0
	v_pk_add_f32 v[54:55], v[54:55], 1.0 op_sel_hi:[1,0]
	s_nop 0
	v_div_scale_f32 v56, s[4:5], v55, v55, v52
	v_rcp_f32_e32 v57, v56
	s_nop 0
	v_fma_f32 v58, -v56, v57, 1.0
	v_fmac_f32_e32 v57, v58, v57
	v_div_scale_f32 v58, vcc, v52, v55, v52
	v_mul_f32_e32 v59, v58, v57
	v_fma_f32 v60, -v56, v59, v58
	v_fmac_f32_e32 v59, v60, v57
	v_fma_f32 v56, -v56, v59, v58
	v_div_fmas_f32 v56, v56, v57, v59
	v_div_fixup_f32 v55, v56, v55, v52
	v_div_scale_f32 v52, s[4:5], v54, v54, v0
	v_rcp_f32_e32 v56, v52
	s_nop 0
	v_fma_f32 v57, -v52, v56, 1.0
	v_fmac_f32_e32 v56, v57, v56
	v_div_scale_f32 v57, vcc, v0, v54, v0
	v_mul_f32_e32 v58, v57, v56
	v_fma_f32 v59, -v52, v58, v57
	v_fmac_f32_e32 v58, v59, v56
	v_fma_f32 v52, -v52, v58, v57
	v_div_fmas_f32 v52, v52, v56, v58
	v_div_fixup_f32 v54, v52, v54, v0
	v_pk_mul_f32 v[34:35], v[34:35], v[54:55]
	v_lshlrev_b32_e32 v0, 16, v53
	v_and_b32_e32 v54, 0xffff0000, v53
	v_mul_f32_e32 v52, 0xbfb8aa3b, v0
	v_mul_f32_e32 v53, 0xbfb8aa3b, v54
	v_exp_f32_e32 v52, v52
	v_exp_f32_e32 v53, v53
	v_cvt_pk_bf16_f32 v34, v34, v35
	v_pk_add_f32 v[52:53], v[52:53], 1.0 op_sel_hi:[1,0]
	s_nop 0
	v_div_scale_f32 v55, s[4:5], v53, v53, v54
	v_rcp_f32_e32 v56, v55
	s_nop 0
	v_fma_f32 v57, -v55, v56, 1.0
	v_fmac_f32_e32 v56, v57, v56
	v_div_scale_f32 v57, vcc, v54, v53, v54
	v_mul_f32_e32 v58, v57, v56
	v_fma_f32 v59, -v55, v58, v57
	v_fmac_f32_e32 v58, v59, v56
	v_fma_f32 v55, -v55, v58, v57
	v_div_fmas_f32 v55, v55, v56, v58
	v_div_fixup_f32 v53, v55, v53, v54
	v_div_scale_f32 v54, s[4:5], v52, v52, v0
	v_rcp_f32_e32 v55, v54
	s_nop 0
	v_fma_f32 v56, -v54, v55, 1.0
	v_fmac_f32_e32 v55, v56, v55
	v_div_scale_f32 v56, vcc, v0, v52, v0
	v_mul_f32_e32 v57, v56, v55
	v_fma_f32 v58, -v54, v57, v56
	v_fmac_f32_e32 v57, v58, v55
	v_fma_f32 v54, -v54, v57, v56
	v_div_fmas_f32 v54, v54, v55, v57
	v_div_fixup_f32 v52, v54, v52, v0
	v_pk_mul_f32 v[36:37], v[36:37], v[52:53]
	s_nop 0
	v_cvt_pk_bf16_f32 v35, v36, v37
	global_store_dwordx2 v[50:51], v[34:35], off offset:64
	v_mov_b32_e32 v36, v122
	v_mov_b32_e32 v37, v123
	v_lshlrev_b32_e32 v0, 16, v36
	v_and_b32_e32 v36, 0xffff0000, v36
	v_mul_f32_e32 v34, 0xbfb8aa3b, v0
	v_mul_f32_e32 v35, 0xbfb8aa3b, v36
	v_exp_f32_e32 v34, v34
	v_exp_f32_e32 v35, v35
	s_nop 0
	v_pk_add_f32 v[34:35], v[34:35], 1.0 op_sel_hi:[1,0]
	s_nop 0
	v_div_scale_f32 v52, s[4:5], v35, v35, v36
	v_rcp_f32_e32 v53, v52
	s_nop 0
	v_fma_f32 v54, -v52, v53, 1.0
	v_fmac_f32_e32 v53, v54, v53
	v_div_scale_f32 v54, vcc, v36, v35, v36
	v_mul_f32_e32 v55, v54, v53
	v_fma_f32 v56, -v52, v55, v54
	v_fmac_f32_e32 v55, v56, v53
	v_fma_f32 v52, -v52, v55, v54
	v_div_fmas_f32 v52, v52, v53, v55
	v_div_fixup_f32 v35, v52, v35, v36
	v_div_scale_f32 v36, s[4:5], v34, v34, v0
	v_rcp_f32_e32 v52, v36
	s_nop 0
	v_fma_f32 v53, -v36, v52, 1.0
	v_fmac_f32_e32 v52, v53, v52
	v_div_scale_f32 v53, vcc, v0, v34, v0
	v_mul_f32_e32 v54, v53, v52
	v_fma_f32 v55, -v36, v54, v53
	v_fmac_f32_e32 v54, v55, v52
	v_fma_f32 v36, -v36, v54, v53
	v_div_fmas_f32 v36, v36, v52, v54
	v_div_fixup_f32 v34, v36, v34, v0
	v_lshlrev_b32_e32 v0, 16, v37
	v_and_b32_e32 v52, 0xffff0000, v37
	v_pk_mul_f32 v[34:35], v[38:39], v[34:35]
	v_mul_f32_e32 v36, 0xbfb8aa3b, v0
	v_mul_f32_e32 v39, 0xbfb8aa3b, v52
	v_exp_f32_e32 v38, v36
	v_exp_f32_e32 v39, v39
	v_pk_mul_f32 v[36:37], v[66:67], v[40:41] op_sel_hi:[0,1]
	v_cvt_pk_bf16_f32 v34, v34, v35
	v_pk_add_f32 v[38:39], v[38:39], 1.0 op_sel_hi:[1,0]
	s_nop 0
	v_div_scale_f32 v40, s[4:5], v39, v39, v52
	v_rcp_f32_e32 v41, v40
	s_nop 0
	v_fma_f32 v53, -v40, v41, 1.0
	v_fmac_f32_e32 v41, v53, v41
	v_div_scale_f32 v53, vcc, v52, v39, v52
	v_mul_f32_e32 v54, v53, v41
	v_fma_f32 v55, -v40, v54, v53
	v_fmac_f32_e32 v54, v55, v41
	v_fma_f32 v40, -v40, v54, v53
	v_div_fmas_f32 v40, v40, v41, v54
	v_div_fixup_f32 v39, v40, v39, v52
	v_div_scale_f32 v40, s[4:5], v38, v38, v0
	v_rcp_f32_e32 v41, v40
	s_nop 0
	v_fma_f32 v52, -v40, v41, 1.0
	v_fmac_f32_e32 v41, v52, v41
	v_div_scale_f32 v52, vcc, v0, v38, v0
	v_mul_f32_e32 v53, v52, v41
	v_fma_f32 v54, -v40, v53, v52
	v_fmac_f32_e32 v53, v54, v41
	v_fma_f32 v40, -v40, v53, v52
	v_div_fmas_f32 v40, v40, v41, v53
	v_div_fixup_f32 v38, v40, v38, v0
	v_pk_mul_f32 v[36:37], v[36:37], v[38:39]
	v_pk_mul_f32 v[38:39], v[66:67], v[42:43] op_sel_hi:[0,1]
	v_cvt_pk_bf16_f32 v35, v36, v37
	global_store_dwordx2 v[50:51], v[34:35], off offset:80
	v_mov_b32_e32 v36, v124
	v_mov_b32_e32 v37, v125
	v_lshlrev_b32_e32 v0, 16, v36
	v_and_b32_e32 v36, 0xffff0000, v36
; DI float silu(float x) { return x / (1.f + __expf(-x)); }
; DI f32x4 unpack4(u32x2 v) { f32x4 r = {bflo(v.x), bfhi(v.x), bflo(v.y), bfhi(v.y)}; return r; }
; DI u32x2 pack4(f32x4 v) { u32x2 r = {cvtpk(v[0], v[1]), cvtpk(v[2], v[3])}; return r; }
; template <int DQK, bool STATIC>
; DI void attn_item8(const bf16_t* __restrict__ Q, const bf16_t* __restrict__ Kp, const bf16_t* __restrict__ Vt, int nkeys, char* lds,
;                   const bf16_t* __restrict__ Pg, bf16_t* __restrict__ Yg  , float mfix) {
;     ...
; #pragma unroll
;   for (int d = 0; d < 2; ++d)
; #pragma unroll
;     for (int q = 0; q < 4; ++q) {
;       const int dv = 32 * d + 8 * q + 4 * h;
;       f32x4 g = unpack4(*(const u32x2*)(Pg + rq * NIN + dv));
;       f32x4 v = {o[d][4 * q] * inv * silu(g[0]), o[d][4 * q + 1] * inv * silu(g[1]), o[d][4 * q + 2] * inv * silu(g[2]), o[d][4 * q + 3] * inv * silu(g[3])};
;       *(u32x2*)(Yg + rq * 1024 + dv) = pack4(v);
;     }
	v_mul_f32_e32 v34, 0xbfb8aa3b, v0
	v_mul_f32_e32 v35, 0xbfb8aa3b, v36
	v_exp_f32_e32 v34, v34
	v_exp_f32_e32 v35, v35
	s_nop 0
	v_pk_add_f32 v[34:35], v[34:35], 1.0 op_sel_hi:[1,0]
	s_nop 0
	v_div_scale_f32 v40, s[4:5], v35, v35, v36
	v_rcp_f32_e32 v41, v40
	s_nop 0
	v_fma_f32 v42, -v40, v41, 1.0
	v_fmac_f32_e32 v41, v42, v41
	v_div_scale_f32 v42, vcc, v36, v35, v36
	v_mul_f32_e32 v43, v42, v41
	v_fma_f32 v52, -v40, v43, v42
	v_fmac_f32_e32 v43, v52, v41
	v_fma_f32 v40, -v40, v43, v42
	v_div_fmas_f32 v40, v40, v41, v43
	v_div_fixup_f32 v35, v40, v35, v36
	v_div_scale_f32 v36, s[4:5], v34, v34, v0
	v_rcp_f32_e32 v40, v36
	s_nop 0
	v_fma_f32 v41, -v36, v40, 1.0
	v_fmac_f32_e32 v40, v41, v40
	v_div_scale_f32 v41, vcc, v0, v34, v0
	v_mul_f32_e32 v42, v41, v40
	v_fma_f32 v43, -v36, v42, v41
	v_fmac_f32_e32 v42, v43, v40
	v_fma_f32 v36, -v36, v42, v41
	v_div_fmas_f32 v36, v36, v40, v42
	v_div_fixup_f32 v34, v36, v34, v0
	v_lshlrev_b32_e32 v0, 16, v37
	v_and_b32_e32 v40, 0xffff0000, v37
	v_pk_mul_f32 v[34:35], v[38:39], v[34:35]
	v_mul_f32_e32 v36, 0xbfb8aa3b, v0
	v_mul_f32_e32 v39, 0xbfb8aa3b, v40
	v_exp_f32_e32 v38, v36
	v_exp_f32_e32 v39, v39
	v_pk_mul_f32 v[36:37], v[66:67], v[44:45] op_sel_hi:[0,1]
	v_cvt_pk_bf16_f32 v34, v34, v35
	v_pk_add_f32 v[38:39], v[38:39], 1.0 op_sel_hi:[1,0]
	s_nop 0
	v_div_scale_f32 v41, s[4:5], v39, v39, v40
	v_rcp_f32_e32 v42, v41
	s_nop 0
	v_fma_f32 v43, -v41, v42, 1.0
	v_fmac_f32_e32 v42, v43, v42
	v_div_scale_f32 v43, vcc, v40, v39, v40
	v_mul_f32_e32 v44, v43, v42
	v_fma_f32 v45, -v41, v44, v43
	v_fmac_f32_e32 v44, v45, v42
	v_fma_f32 v41, -v41, v44, v43
	v_div_fmas_f32 v41, v41, v42, v44
	v_div_fixup_f32 v39, v41, v39, v40
	v_div_scale_f32 v40, s[4:5], v38, v38, v0
	v_rcp_f32_e32 v41, v40
	s_nop 0
	v_fma_f32 v42, -v40, v41, 1.0
	v_fmac_f32_e32 v41, v42, v41
	v_div_scale_f32 v42, vcc, v0, v38, v0
	v_mul_f32_e32 v43, v42, v41
	v_fma_f32 v44, -v40, v43, v42
	v_fmac_f32_e32 v43, v44, v41
	v_fma_f32 v40, -v40, v43, v42
	v_div_fmas_f32 v40, v40, v41, v43
	v_div_fixup_f32 v38, v40, v38, v0
	v_pk_mul_f32 v[36:37], v[36:37], v[38:39]
	v_pk_mul_f32 v[38:39], v[66:67], v[46:47] op_sel_hi:[0,1]
	v_cvt_pk_bf16_f32 v35, v36, v37
	global_store_dwordx2 v[50:51], v[34:35], off offset:96
	v_mov_b32_e32 v34, v126
	v_mov_b32_e32 v35, v127
	v_lshlrev_b32_e32 v0, 16, v34
	v_and_b32_e32 v34, 0xffff0000, v34
	v_mul_f32_e32 v36, 0xbfb8aa3b, v0
	v_mul_f32_e32 v37, 0xbfb8aa3b, v34
	v_exp_f32_e32 v36, v36
	v_exp_f32_e32 v37, v37
	s_nop 0
	v_pk_add_f32 v[36:37], v[36:37], 1.0 op_sel_hi:[1,0]
	s_nop 0
	v_div_scale_f32 v40, s[4:5], v37, v37, v34
	v_rcp_f32_e32 v41, v40
	s_nop 0
	v_fma_f32 v42, -v40, v41, 1.0
	v_fmac_f32_e32 v41, v42, v41
	v_div_scale_f32 v42, vcc, v34, v37, v34
	v_mul_f32_e32 v43, v42, v41
	v_fma_f32 v44, -v40, v43, v42
	v_fmac_f32_e32 v43, v44, v41
	v_fma_f32 v40, -v40, v43, v42
	v_div_fmas_f32 v40, v40, v41, v43
	v_div_fixup_f32 v37, v40, v37, v34
	v_div_scale_f32 v34, s[4:5], v36, v36, v0
	v_rcp_f32_e32 v40, v34
	s_nop 0
	v_fma_f32 v41, -v34, v40, 1.0
	v_fmac_f32_e32 v40, v41, v40
	v_div_scale_f32 v41, vcc, v0, v36, v0
	v_mul_f32_e32 v42, v41, v40
	v_fma_f32 v43, -v34, v42, v41
	v_fmac_f32_e32 v42, v43, v40
	v_fma_f32 v34, -v34, v42, v41
	v_div_fmas_f32 v34, v34, v40, v42
	v_div_fixup_f32 v36, v34, v36, v0
	v_lshlrev_b32_e32 v0, 16, v35
	v_and_b32_e32 v40, 0xffff0000, v35
	v_mul_f32_e32 v34, 0xbfb8aa3b, v0
	v_mul_f32_e32 v35, 0xbfb8aa3b, v40
	v_exp_f32_e32 v34, v34
	v_exp_f32_e32 v35, v35
	v_pk_mul_f32 v[36:37], v[38:39], v[36:37]
	v_pk_mul_f32 v[38:39], v[66:67], v[48:49] op_sel_hi:[0,1]
	v_cvt_pk_bf16_f32 v36, v36, v37
	v_pk_add_f32 v[34:35], v[34:35], 1.0 op_sel_hi:[1,0]
	s_nop 0
	v_div_scale_f32 v41, s[4:5], v35, v35, v40
	v_rcp_f32_e32 v42, v41
	s_nop 0
	v_fma_f32 v43, -v41, v42, 1.0
	v_fmac_f32_e32 v42, v43, v42
	v_div_scale_f32 v43, vcc, v40, v35, v40
	v_mul_f32_e32 v44, v43, v42
	v_fma_f32 v45, -v41, v44, v43
	v_fmac_f32_e32 v44, v45, v42
	v_fma_f32 v41, -v41, v44, v43
	v_div_fmas_f32 v41, v41, v42, v44
	v_div_fixup_f32 v35, v41, v35, v40
	v_div_scale_f32 v40, s[4:5], v34, v34, v0
	v_rcp_f32_e32 v41, v40
	s_nop 0
	v_fma_f32 v42, -v40, v41, 1.0
	v_fmac_f32_e32 v41, v42, v41
	v_div_scale_f32 v42, vcc, v0, v34, v0
	v_mul_f32_e32 v43, v42, v41
	v_fma_f32 v44, -v40, v43, v42
	v_fmac_f32_e32 v43, v44, v41
	v_fma_f32 v40, -v40, v43, v42
	v_div_fmas_f32 v40, v40, v41, v43
	v_div_fixup_f32 v34, v40, v34, v0
	v_pk_mul_f32 v[34:35], v[38:39], v[34:35]
	s_nop 0
	v_cvt_pk_bf16_f32 v37, v34, v35
	global_store_dwordx2 v[50:51], v[36:37], off offset:112
	s_cbranch_scc1 .LBB0_123

; DI f32x4 unpack4(u32x2 v) { f32x4 r = {bflo(v.x), bfhi(v.x), bflo(v.y), bfhi(v.y)}; return r; }
; template <int DQK, bool STATIC>
; DI void attn_item8(const bf16_t* __restrict__ Q, const bf16_t* __restrict__ Kp, const bf16_t* __restrict__ Vt, int nkeys, char* lds,
;                   const bf16_t* __restrict__ Pg, bf16_t* __restrict__ Yg  , float mfix) {
;     ...
;     if (more) {
; #pragma unroll
;       for (int i = 0; i < NKC; ++i) rk[i] = *(const u32x4*)(Kp + (size_t)(j + 1) * 64 * DQK + koffg[i]);
; #pragma unroll
;       for (int i = 0; i < 1; ++i) rv[i] = *(const u32x4*)(vg + (size_t)i * 32 * T + (j + 1) * 64);
;     }
;     ...
;       f32x4 g = unpack4(*(const u32x2*)(Pg + rq * NIN + dv));
.Lab_nodef:
	s_cmp_lt_u32 s49, s65
	s_cbranch_scc1 .Lab_doload
	v_mov_b64_e32 v[140:141], s[36:37]
	v_mad_u64_u32 v[140:141], vcc, v188, s11, v[140:141]
	v_lshlrev_b32_e32 v139, 3, v187
	v_add_co_u32_e32 v140, vcc, v139, v140
	s_nop 1
	v_addc_co_u32_e32 v141, vcc, 0, v141, vcc
	global_load_dwordx2 v[170:171], v[140:141], off
	global_load_dwordx2 v[172:173], v[140:141], off offset:16
	global_load_dwordx2 v[174:175], v[140:141], off offset:32
	global_load_dwordx2 v[176:177], v[140:141], off offset:48
	global_load_dwordx2 v[178:179], v[140:141], off offset:64
	global_load_dwordx2 v[180:181], v[140:141], off offset:80
	global_load_dwordx2 v[182:183], v[140:141], off offset:96
	global_load_dwordx2 v[184:185], v[140:141], off offset:112
	s_branch .Lab_noload
.Lab_doload:
	s_lshl_b32 s52, s49, 14
	s_mov_b32 s53, 0
	v_lshl_add_u64 v[140:141], v[124:125], 0, s[52:53]
	global_load_dwordx4 v[114:117], v[140:141], off
	s_add_u32 s52, s52, 0x2000
	v_lshl_add_u64 v[140:141], v[124:125], 0, s[52:53]
	global_load_dwordx4 v[162:165], v[140:141], off
	s_lshl_b32 s52, s49, 8
	v_lshl_add_u64 v[140:141], v[122:123], 0, s[52:53]
	global_load_dwordx4 v[118:121], v[140:141], off
	global_load_dwordx4 v[166:169], v[140:141], off offset:128

; DI unsigned cvtpk(float lo, float hi) { f32x2 v = {lo, hi}; bf16x2_t b = __builtin_convertvector(v, bf16x2_t); return __builtin_bit_cast(unsigned, b); }
; DI f32x4 unpack4(u32x2 v) { f32x4 r = {bflo(v.x), bfhi(v.x), bflo(v.y), bfhi(v.y)}; return r; }
; #define MFMA32(a, b, c) __builtin_amdgcn_mfma_f32_32x32x16_bf16((a), (b), (c), 0, 0, 0)
; template <int DQK, bool STATIC>
; DI void attn_item8(const bf16_t* __restrict__ Q, const bf16_t* __restrict__ Kp, const bf16_t* __restrict__ Vt, int nkeys, char* lds,
;                   const bf16_t* __restrict__ Pg, bf16_t* __restrict__ Yg  , float mfix) {
;     ...
;     {
;       float ps = 0.f;
; #pragma unroll
;       for (int e = 0; e < 16; ++e) { float p = STATIC ? __builtin_amdgcn_exp2f(s1[e]) : __builtin_amdgcn_exp2f(s1[e] - m_run); s1[e] = p; ps += p; }
;       l_run += ps;
;     }
; #pragma unroll
;     for (int s2 = 0; s2 < 2; ++s2) {
;       u32x4 pw = {cvtpk(s1[8 * s2], s1[8 * s2 + 1]), cvtpk(s1[8 * s2 + 2], s1[8 * s2 + 3]), cvtpk(s1[8 * s2 + 4], s1[8 * s2 + 5]), cvtpk(s1[8 * s2 + 6], s1[8 * s2 + 7])};
;       bf16x8 pf = __builtin_bit_cast(bf16x8, pw);
; #pragma unroll
;       for (int d = 0; d < 2; ++d) o[d] = MFMA32(__builtin_bit_cast(bf16x8, vw[1][s2][d]), pf, o[d]);
;     }
;     if (more) {
;       char* nxt = nxtp + sub * BUF;
; #pragma unroll
;       for (int i = 0; i < NKC; ++i) if (koffl[i] >= 0) *(u32x4*)(nxt + koffl[i]) = rk[i];
; #pragma unroll
;       for (int i = 0; i < 1; ++i) { u32x2 a = {rv[i].x, rv[i].y}, b = {rv[i].z, rv[i].w}; *(u32x2*)(nxt + voffl + i * 32 * VSTR) = a; *(u32x2*)(nxt + voffl + i * 32 * VSTR + 8) = b; }
;     }
;    }
;    __syncthreads();
;   }
;   const float lt = l_run + __shfl_xor(l_run, 32);
;     ...
;       f32x4 g = unpack4(*(const u32x2*)(Pg + rq * NIN + dv));
.Lab_nostage1:
.Lab_pairend:
	s_cmp_eq_u32 s49, s65
	s_waitcnt lgkmcnt(0)
	s_barrier
	s_cbranch_scc0 .LBB0_45
	v_add_f32_e32 v137, v66, v68
	v_add_f32_e32 v138, v67, v69
	v_add_f32_e32 v137, v70, v137
	v_add_f32_e32 v138, v71, v138
	v_add_f32_e32 v137, v72, v137
	v_add_f32_e32 v138, v73, v138
	v_add_f32_e32 v137, v74, v137
	v_add_f32_e32 v138, v75, v138
	v_add_f32_e32 v137, v76, v137
	v_add_f32_e32 v138, v77, v138
	v_add_f32_e32 v137, v78, v137
	v_add_f32_e32 v138, v79, v138
	v_add_f32_e32 v137, v80, v137
	v_add_f32_e32 v138, v81, v138
	v_add_f32_e32 v137, v137, v138
	v_add_f32_e32 v215, v215, v137
	s_nop 7
	s_setprio 0
	s_waitcnt vmcnt(0)
	v_mov_b32_e32 v112, v170
	v_mov_b32_e32 v113, v171
	v_mov_b32_e32 v114, v172
	v_mov_b32_e32 v115, v173
	v_mov_b32_e32 v116, v174
	v_mov_b32_e32 v117, v175
	v_mov_b32_e32 v118, v176
	v_mov_b32_e32 v119, v177
	v_mov_b32_e32 v120, v178
	v_mov_b32_e32 v121, v179
	v_mov_b32_e32 v122, v180
	v_mov_b32_e32 v123, v181
	v_mov_b32_e32 v124, v182
	v_mov_b32_e32 v125, v183
	v_mov_b32_e32 v126, v184
	v_mov_b32_e32 v127, v185
	s_mov_b32 s100, 1

; DI f32x4 unpack4(u32x2 v) { f32x4 r = {bflo(v.x), bfhi(v.x), bflo(v.y), bfhi(v.y)}; return r; }
; template <int DQK, bool STATIC>
; DI void attn_item8(const bf16_t* __restrict__ Q, const bf16_t* __restrict__ Kp, const bf16_t* __restrict__ Vt, int nkeys, char* lds,
;                   const bf16_t* __restrict__ Pg, bf16_t* __restrict__ Yg  , float mfix) {
;     ...
;     if (more) {
; #pragma unroll
;       for (int i = 0; i < NKC; ++i) rk[i] = *(const u32x4*)(Kp + (size_t)(j + 1) * 64 * DQK + koffg[i]);
; #pragma unroll
;       for (int i = 0; i < 1; ++i) rv[i] = *(const u32x4*)(vg + (size_t)i * 32 * T + (j + 1) * 64);
;     }
;     ...
;       f32x4 g = unpack4(*(const u32x2*)(Pg + rq * NIN + dv));
.Laa_nodef:
	s_cmp_lt_u32 s2, s65
	s_cbranch_scc1 .Laa_doload
	v_mov_b64_e32 v[194:195], s[36:37]
	v_mad_u64_u32 v[194:195], vcc, v188, s11, v[194:195]
	v_lshlrev_b32_e32 v203, 3, v187
	v_add_co_u32_e32 v194, vcc, v203, v194
	s_nop 1
	v_addc_co_u32_e32 v195, vcc, 0, v195, vcc
	global_load_dwordx2 v[146:147], v[194:195], off
	global_load_dwordx2 v[148:149], v[194:195], off offset:16
	global_load_dwordx2 v[150:151], v[194:195], off offset:32
	global_load_dwordx2 v[152:153], v[194:195], off offset:48
	global_load_dwordx2 v[154:155], v[194:195], off offset:64
	global_load_dwordx2 v[156:157], v[194:195], off offset:80
	global_load_dwordx2 v[210:211], v[194:195], off offset:96
	global_load_dwordx2 v[212:213], v[194:195], off offset:112
	s_branch .Laa_noload
.Laa_doload:
	s_lshl_b32 s52, s2, 1
	s_mul_i32 s52, s52, 0x3000
	s_add_u32 s52, s56, s52
	s_addc_u32 s53, s57, 0
	v_lshl_add_u64 v[194:195], v[138:139], 1, s[52:53]
	v_lshl_add_u64 v[248:249], v[134:135], 1, s[52:53]
	global_load_dwordx4 v[122:125], v[194:195], off
	global_load_dwordx4 v[126:129], v[248:249], off
	s_add_u32 s52, s52, 0x3000
	s_addc_u32 s53, s53, 0
	v_lshl_add_u64 v[194:195], v[138:139], 1, s[52:53]
	v_lshl_add_u64 v[248:249], v[134:135], 1, s[52:53]
	global_load_dwordx4 v[146:149], v[194:195], off
	global_load_dwordx4 v[150:153], v[248:249], off
	s_lshl_b32 s74, s2, 8
	s_mov_b32 s75, 0
	v_lshl_add_u64 v[194:195], v[136:137], 0, s[74:75]
	global_load_dwordx4 v[130:133], v[194:195], off
	global_load_dwordx4 v[154:157], v[194:195], off offset:128

; DI unsigned cvtpk(float lo, float hi) { f32x2 v = {lo, hi}; bf16x2_t b = __builtin_convertvector(v, bf16x2_t); return __builtin_bit_cast(unsigned, b); }
; DI f32x4 unpack4(u32x2 v) { f32x4 r = {bflo(v.x), bfhi(v.x), bflo(v.y), bfhi(v.y)}; return r; }
; #define MFMA32(a, b, c) __builtin_amdgcn_mfma_f32_32x32x16_bf16((a), (b), (c), 0, 0, 0)
; template <int DQK, bool STATIC>
; DI void attn_item8(const bf16_t* __restrict__ Q, const bf16_t* __restrict__ Kp, const bf16_t* __restrict__ Vt, int nkeys, char* lds,
;                   const bf16_t* __restrict__ Pg, bf16_t* __restrict__ Yg  , float mfix) {
;     ...
;     {
;       float ps = 0.f;
; #pragma unroll
;       for (int e = 0; e < 16; ++e) { float p = STATIC ? __builtin_amdgcn_exp2f(s1[e]) : __builtin_amdgcn_exp2f(s1[e] - m_run); s1[e] = p; ps += p; }
;       l_run += ps;
;     }
; #pragma unroll
;     for (int s2 = 0; s2 < 2; ++s2) {
;       u32x4 pw = {cvtpk(s1[8 * s2], s1[8 * s2 + 1]), cvtpk(s1[8 * s2 + 2], s1[8 * s2 + 3]), cvtpk(s1[8 * s2 + 4], s1[8 * s2 + 5]), cvtpk(s1[8 * s2 + 6], s1[8 * s2 + 7])};
;       bf16x8 pf = __builtin_bit_cast(bf16x8, pw);
; #pragma unroll
;       for (int d = 0; d < 2; ++d) o[d] = MFMA32(__builtin_bit_cast(bf16x8, vw[1][s2][d]), pf, o[d]);
;     }
;     if (more) {
;       char* nxt = nxtp + sub * BUF;
; #pragma unroll
;       for (int i = 0; i < NKC; ++i) if (koffl[i] >= 0) *(u32x4*)(nxt + koffl[i]) = rk[i];
; #pragma unroll
;       for (int i = 0; i < 1; ++i) { u32x2 a = {rv[i].x, rv[i].y}, b = {rv[i].z, rv[i].w}; *(u32x2*)(nxt + voffl + i * 32 * VSTR) = a; *(u32x2*)(nxt + voffl + i * 32 * VSTR + 8) = b; }
;     }
;    }
;    __syncthreads();
;   }
;   const float lt = l_run + __shfl_xor(l_run, 32);
;     ...
;       f32x4 g = unpack4(*(const u32x2*)(Pg + rq * NIN + dv));
.Laa_nostage1:
.Laa_pairend:
	s_cmp_eq_u32 s2, s65
	s_waitcnt lgkmcnt(0)
	s_barrier
	s_cbranch_scc0 .LBB0_87
	v_add_f32_e32 v192, v66, v68
	v_add_f32_e32 v193, v67, v69
	v_add_f32_e32 v192, v70, v192
	v_add_f32_e32 v193, v71, v193
	v_add_f32_e32 v192, v72, v192
	v_add_f32_e32 v193, v73, v193
	v_add_f32_e32 v192, v74, v192
	v_add_f32_e32 v193, v75, v193
	v_add_f32_e32 v192, v76, v192
	v_add_f32_e32 v193, v77, v193
	v_add_f32_e32 v192, v78, v192
	v_add_f32_e32 v193, v79, v193
	v_add_f32_e32 v192, v80, v192
	v_add_f32_e32 v193, v81, v193
	v_add_f32_e32 v192, v192, v193
	v_add_f32_e32 v215, v215, v192
	s_nop 7
	s_setprio 0
	s_waitcnt vmcnt(0)
	v_mov_b32_e32 v112, v146
	v_mov_b32_e32 v113, v147
	v_mov_b32_e32 v114, v148
	v_mov_b32_e32 v115, v149
	v_mov_b32_e32 v116, v150
	v_mov_b32_e32 v117, v151
	v_mov_b32_e32 v118, v152
	v_mov_b32_e32 v119, v153
	v_mov_b32_e32 v120, v154
	v_mov_b32_e32 v121, v155
	v_mov_b32_e32 v122, v156
	v_mov_b32_e32 v123, v157
	v_mov_b32_e32 v124, v210
	v_mov_b32_e32 v125, v211
	v_mov_b32_e32 v126, v212
	v_mov_b32_e32 v127, v213
	s_mov_b32 s100, 1
